# gate-weight folding inner loops unrolled over two register sets with counted vmcnt (loads of iteration k+1 in flight during iteration k)
# baseline (speedup 1.0000x reference)
.LBB0_44:
	v_ashrrev_i32_e32 v2, 31, v51
	v_lshrrev_b32_e32 v2, 21, v2
	v_add_u32_e32 v2, v51, v2
	v_and_b32_e32 v2, 0xfffff800, v2
	v_sub_u32_e32 v8, v51, v2
	v_cmp_lt_i32_e64 s[6:7], s3, v51
	v_ashrrev_i32_e32 v9, 31, v8
	s_waitcnt lgkmcnt(0)
	v_lshlrev_b64 v[18:19], 13, v[8:9]
	v_cndmask_b32_e64 v11, v31, v32, s[6:7]
	v_cndmask_b32_e64 v10, v33, v34, s[6:7]
	v_cndmask_b32_e64 v2, 0, v30, s[6:7]
	v_lshl_add_u64 v[10:11], v[10:11], 0, v[46:47]
	v_cmp_gt_i32_e32 vcc, s1, v51
	v_lshl_add_u64 v[20:21], v[4:5], 0, v[2:3]
	v_lshl_add_u64 v[22:23], v[10:11], 0, v[18:19]
	s_mov_b64 s[12:13], 0
	v_mov_b32_e32 v16, 0
	v_mov_b32_e32 v17, v3
	v_mov_b32_e32 v14, 0
	v_mov_b32_e32 v15, v3
	v_mov_b32_e32 v12, 0
	v_mov_b32_e32 v13, v3
	v_mov_b32_e32 v10, 0
	v_mov_b32_e32 v11, v3
	s_mov_b32 s62, 0x1000
	s_mov_b32 s63, 0
	v_mov_b32_e32 v242, v20
	v_mov_b32_e32 v243, v21
	global_load_dword v210, v[22:23], off
	global_load_dword v212, v[22:23], off offset:256
	global_load_dword v214, v[22:23], off offset:512
	global_load_dword v216, v[22:23], off offset:768
	global_load_dword v218, v[22:23], off offset:1024
	global_load_dword v220, v[22:23], off offset:1280
	global_load_dword v222, v[22:23], off offset:1536
	global_load_dword v224, v[22:23], off offset:1792
	v_lshl_add_u64 v[22:23], v[22:23], 0, s[8:9]
	global_load_dwordx4 v[126:129], v[242:243], off
	global_load_dwordx4 v[130:133], v[242:243], off offset:16
	global_load_dwordx4 v[134:137], v[242:243], off offset:2048
	global_load_dwordx4 v[138:141], v[242:243], off offset:2064
	v_lshl_add_u64 v[242:243], v[242:243], 0, s[62:63]
	global_load_dwordx4 v[142:145], v[242:243], off
	global_load_dwordx4 v[146:149], v[242:243], off offset:16
	global_load_dwordx4 v[150:153], v[242:243], off offset:2048
	global_load_dwordx4 v[154:157], v[242:243], off offset:2064
	v_lshl_add_u64 v[242:243], v[242:243], 0, s[62:63]
	global_load_dwordx4 v[158:161], v[242:243], off
	global_load_dwordx4 v[162:165], v[242:243], off offset:16
	global_load_dwordx4 v[166:169], v[242:243], off offset:2048
	global_load_dwordx4 v[170:173], v[242:243], off offset:2064
	v_lshl_add_u64 v[242:243], v[242:243], 0, s[62:63]
	global_load_dwordx4 v[174:177], v[242:243], off
	global_load_dwordx4 v[178:181], v[242:243], off offset:16
	global_load_dwordx4 v[182:185], v[242:243], off offset:2048
	global_load_dwordx4 v[186:189], v[242:243], off offset:2064
	v_lshl_add_u64 v[242:243], v[242:243], 0, s[62:63]
	global_load_dword v226, v[22:23], off
	global_load_dword v228, v[22:23], off offset:256
	global_load_dword v230, v[22:23], off offset:512
	global_load_dword v232, v[22:23], off offset:768
	global_load_dword v234, v[22:23], off offset:1024
	global_load_dword v236, v[22:23], off offset:1280
	global_load_dword v238, v[22:23], off offset:1536
	global_load_dword v240, v[22:23], off offset:1792
	v_lshl_add_u64 v[22:23], v[22:23], 0, s[8:9]
	global_load_dwordx4 v[52:55], v[242:243], off
	global_load_dwordx4 v[56:59], v[242:243], off offset:16
	global_load_dwordx4 v[60:63], v[242:243], off offset:2048
	global_load_dwordx4 v[64:67], v[242:243], off offset:2064
	v_lshl_add_u64 v[242:243], v[242:243], 0, s[62:63]
	global_load_dwordx4 v[68:71], v[242:243], off
	global_load_dwordx4 v[72:75], v[242:243], off offset:16
	global_load_dwordx4 v[76:79], v[242:243], off offset:2048
	global_load_dwordx4 v[80:83], v[242:243], off offset:2064
	v_lshl_add_u64 v[242:243], v[242:243], 0, s[62:63]
	global_load_dwordx4 v[84:87], v[242:243], off
	global_load_dwordx4 v[88:91], v[242:243], off offset:16
	global_load_dwordx4 v[92:95], v[242:243], off offset:2048
	global_load_dwordx4 v[96:99], v[242:243], off offset:2064
	v_lshl_add_u64 v[242:243], v[242:243], 0, s[62:63]
	global_load_dwordx4 v[100:103], v[242:243], off
	global_load_dwordx4 v[104:107], v[242:243], off offset:16
	global_load_dwordx4 v[108:111], v[242:243], off offset:2048
	global_load_dwordx4 v[112:115], v[242:243], off offset:2064
	v_lshl_add_u64 v[242:243], v[242:243], 0, s[62:63]
	s_waitcnt vmcnt(24)
	v_pk_fma_f32 v[16:17], v[210:211], v[126:127], v[16:17] op_sel_hi:[0,1,1]
	v_pk_fma_f32 v[14:15], v[210:211], v[128:129], v[14:15] op_sel_hi:[0,1,1]
	v_pk_fma_f32 v[12:13], v[210:211], v[130:131], v[12:13] op_sel_hi:[0,1,1]
	v_pk_fma_f32 v[10:11], v[210:211], v[132:133], v[10:11] op_sel_hi:[0,1,1]
	v_pk_fma_f32 v[16:17], v[212:213], v[134:135], v[16:17] op_sel_hi:[0,1,1]
	v_pk_fma_f32 v[14:15], v[212:213], v[136:137], v[14:15] op_sel_hi:[0,1,1]
	v_pk_fma_f32 v[12:13], v[212:213], v[138:139], v[12:13] op_sel_hi:[0,1,1]
	v_pk_fma_f32 v[10:11], v[212:213], v[140:141], v[10:11] op_sel_hi:[0,1,1]
	v_pk_fma_f32 v[16:17], v[214:215], v[142:143], v[16:17] op_sel_hi:[0,1,1]
	v_pk_fma_f32 v[14:15], v[214:215], v[144:145], v[14:15] op_sel_hi:[0,1,1]
	v_pk_fma_f32 v[12:13], v[214:215], v[146:147], v[12:13] op_sel_hi:[0,1,1]
	v_pk_fma_f32 v[10:11], v[214:215], v[148:149], v[10:11] op_sel_hi:[0,1,1]
	v_pk_fma_f32 v[16:17], v[216:217], v[150:151], v[16:17] op_sel_hi:[0,1,1]
	v_pk_fma_f32 v[14:15], v[216:217], v[152:153], v[14:15] op_sel_hi:[0,1,1]
	v_pk_fma_f32 v[12:13], v[216:217], v[154:155], v[12:13] op_sel_hi:[0,1,1]
	v_pk_fma_f32 v[10:11], v[216:217], v[156:157], v[10:11] op_sel_hi:[0,1,1]
	v_pk_fma_f32 v[16:17], v[218:219], v[158:159], v[16:17] op_sel_hi:[0,1,1]
	v_pk_fma_f32 v[14:15], v[218:219], v[160:161], v[14:15] op_sel_hi:[0,1,1]
	v_pk_fma_f32 v[12:13], v[218:219], v[162:163], v[12:13] op_sel_hi:[0,1,1]
	v_pk_fma_f32 v[10:11], v[218:219], v[164:165], v[10:11] op_sel_hi:[0,1,1]
	v_pk_fma_f32 v[16:17], v[220:221], v[166:167], v[16:17] op_sel_hi:[0,1,1]
	v_pk_fma_f32 v[14:15], v[220:221], v[168:169], v[14:15] op_sel_hi:[0,1,1]
	v_pk_fma_f32 v[12:13], v[220:221], v[170:171], v[12:13] op_sel_hi:[0,1,1]
	v_pk_fma_f32 v[10:11], v[220:221], v[172:173], v[10:11] op_sel_hi:[0,1,1]
	v_pk_fma_f32 v[16:17], v[222:223], v[174:175], v[16:17] op_sel_hi:[0,1,1]
	v_pk_fma_f32 v[14:15], v[222:223], v[176:177], v[14:15] op_sel_hi:[0,1,1]
	v_pk_fma_f32 v[12:13], v[222:223], v[178:179], v[12:13] op_sel_hi:[0,1,1]
	v_pk_fma_f32 v[10:11], v[222:223], v[180:181], v[10:11] op_sel_hi:[0,1,1]
	v_pk_fma_f32 v[16:17], v[224:225], v[182:183], v[16:17] op_sel_hi:[0,1,1]
	v_pk_fma_f32 v[14:15], v[224:225], v[184:185], v[14:15] op_sel_hi:[0,1,1]
	v_pk_fma_f32 v[12:13], v[224:225], v[186:187], v[12:13] op_sel_hi:[0,1,1]
	v_pk_fma_f32 v[10:11], v[224:225], v[188:189], v[10:11] op_sel_hi:[0,1,1]
	global_load_dword v210, v[22:23], off
	global_load_dword v212, v[22:23], off offset:256
	global_load_dword v214, v[22:23], off offset:512
	global_load_dword v216, v[22:23], off offset:768
	global_load_dword v218, v[22:23], off offset:1024
	global_load_dword v220, v[22:23], off offset:1280
	global_load_dword v222, v[22:23], off offset:1536
	global_load_dword v224, v[22:23], off offset:1792
	v_lshl_add_u64 v[22:23], v[22:23], 0, s[8:9]
	global_load_dwordx4 v[126:129], v[242:243], off
	global_load_dwordx4 v[130:133], v[242:243], off offset:16
	global_load_dwordx4 v[134:137], v[242:243], off offset:2048
	global_load_dwordx4 v[138:141], v[242:243], off offset:2064
	v_lshl_add_u64 v[242:243], v[242:243], 0, s[62:63]
	global_load_dwordx4 v[142:145], v[242:243], off
	global_load_dwordx4 v[146:149], v[242:243], off offset:16
	global_load_dwordx4 v[150:153], v[242:243], off offset:2048
	global_load_dwordx4 v[154:157], v[242:243], off offset:2064
	v_lshl_add_u64 v[242:243], v[242:243], 0, s[62:63]
	global_load_dwordx4 v[158:161], v[242:243], off
	global_load_dwordx4 v[162:165], v[242:243], off offset:16
	global_load_dwordx4 v[166:169], v[242:243], off offset:2048
	global_load_dwordx4 v[170:173], v[242:243], off offset:2064
	v_lshl_add_u64 v[242:243], v[242:243], 0, s[62:63]
	global_load_dwordx4 v[174:177], v[242:243], off
	global_load_dwordx4 v[178:181], v[242:243], off offset:16
	global_load_dwordx4 v[182:185], v[242:243], off offset:2048
	global_load_dwordx4 v[186:189], v[242:243], off offset:2064
	v_lshl_add_u64 v[242:243], v[242:243], 0, s[62:63]
	s_waitcnt vmcnt(24)
	v_pk_fma_f32 v[16:17], v[226:227], v[52:53], v[16:17] op_sel_hi:[0,1,1]
	v_pk_fma_f32 v[14:15], v[226:227], v[54:55], v[14:15] op_sel_hi:[0,1,1]
	v_pk_fma_f32 v[12:13], v[226:227], v[56:57], v[12:13] op_sel_hi:[0,1,1]
	v_pk_fma_f32 v[10:11], v[226:227], v[58:59], v[10:11] op_sel_hi:[0,1,1]
	v_pk_fma_f32 v[16:17], v[228:229], v[60:61], v[16:17] op_sel_hi:[0,1,1]
	v_pk_fma_f32 v[14:15], v[228:229], v[62:63], v[14:15] op_sel_hi:[0,1,1]
	v_pk_fma_f32 v[12:13], v[228:229], v[64:65], v[12:13] op_sel_hi:[0,1,1]
	v_pk_fma_f32 v[10:11], v[228:229], v[66:67], v[10:11] op_sel_hi:[0,1,1]
	v_pk_fma_f32 v[16:17], v[230:231], v[68:69], v[16:17] op_sel_hi:[0,1,1]
	v_pk_fma_f32 v[14:15], v[230:231], v[70:71], v[14:15] op_sel_hi:[0,1,1]
	v_pk_fma_f32 v[12:13], v[230:231], v[72:73], v[12:13] op_sel_hi:[0,1,1]
	v_pk_fma_f32 v[10:11], v[230:231], v[74:75], v[10:11] op_sel_hi:[0,1,1]
	v_pk_fma_f32 v[16:17], v[232:233], v[76:77], v[16:17] op_sel_hi:[0,1,1]
	v_pk_fma_f32 v[14:15], v[232:233], v[78:79], v[14:15] op_sel_hi:[0,1,1]
	v_pk_fma_f32 v[12:13], v[232:233], v[80:81], v[12:13] op_sel_hi:[0,1,1]
	v_pk_fma_f32 v[10:11], v[232:233], v[82:83], v[10:11] op_sel_hi:[0,1,1]
	v_pk_fma_f32 v[16:17], v[234:235], v[84:85], v[16:17] op_sel_hi:[0,1,1]
	v_pk_fma_f32 v[14:15], v[234:235], v[86:87], v[14:15] op_sel_hi:[0,1,1]
	v_pk_fma_f32 v[12:13], v[234:235], v[88:89], v[12:13] op_sel_hi:[0,1,1]
	v_pk_fma_f32 v[10:11], v[234:235], v[90:91], v[10:11] op_sel_hi:[0,1,1]
	v_pk_fma_f32 v[16:17], v[236:237], v[92:93], v[16:17] op_sel_hi:[0,1,1]
	v_pk_fma_f32 v[14:15], v[236:237], v[94:95], v[14:15] op_sel_hi:[0,1,1]
	v_pk_fma_f32 v[12:13], v[236:237], v[96:97], v[12:13] op_sel_hi:[0,1,1]
	v_pk_fma_f32 v[10:11], v[236:237], v[98:99], v[10:11] op_sel_hi:[0,1,1]
	v_pk_fma_f32 v[16:17], v[238:239], v[100:101], v[16:17] op_sel_hi:[0,1,1]
	v_pk_fma_f32 v[14:15], v[238:239], v[102:103], v[14:15] op_sel_hi:[0,1,1]
	v_pk_fma_f32 v[12:13], v[238:239], v[104:105], v[12:13] op_sel_hi:[0,1,1]
	v_pk_fma_f32 v[10:11], v[238:239], v[106:107], v[10:11] op_sel_hi:[0,1,1]
	v_pk_fma_f32 v[16:17], v[240:241], v[108:109], v[16:17] op_sel_hi:[0,1,1]
	v_pk_fma_f32 v[14:15], v[240:241], v[110:111], v[14:15] op_sel_hi:[0,1,1]
	v_pk_fma_f32 v[12:13], v[240:241], v[112:113], v[12:13] op_sel_hi:[0,1,1]
	v_pk_fma_f32 v[10:11], v[240:241], v[114:115], v[10:11] op_sel_hi:[0,1,1]
	global_load_dword v226, v[22:23], off
	global_load_dword v228, v[22:23], off offset:256
	global_load_dword v230, v[22:23], off offset:512
	global_load_dword v232, v[22:23], off offset:768
	global_load_dword v234, v[22:23], off offset:1024
	global_load_dword v236, v[22:23], off offset:1280
	global_load_dword v238, v[22:23], off offset:1536
	global_load_dword v240, v[22:23], off offset:1792
	v_lshl_add_u64 v[22:23], v[22:23], 0, s[8:9]
	global_load_dwordx4 v[52:55], v[242:243], off
	global_load_dwordx4 v[56:59], v[242:243], off offset:16
	global_load_dwordx4 v[60:63], v[242:243], off offset:2048
	global_load_dwordx4 v[64:67], v[242:243], off offset:2064
	v_lshl_add_u64 v[242:243], v[242:243], 0, s[62:63]
	global_load_dwordx4 v[68:71], v[242:243], off
	global_load_dwordx4 v[72:75], v[242:243], off offset:16
	global_load_dwordx4 v[76:79], v[242:243], off offset:2048
	global_load_dwordx4 v[80:83], v[242:243], off offset:2064
	v_lshl_add_u64 v[242:243], v[242:243], 0, s[62:63]
	global_load_dwordx4 v[84:87], v[242:243], off
	global_load_dwordx4 v[88:91], v[242:243], off offset:16
	global_load_dwordx4 v[92:95], v[242:243], off offset:2048
	global_load_dwordx4 v[96:99], v[242:243], off offset:2064
	v_lshl_add_u64 v[242:243], v[242:243], 0, s[62:63]
	global_load_dwordx4 v[100:103], v[242:243], off
	global_load_dwordx4 v[104:107], v[242:243], off offset:16
	global_load_dwordx4 v[108:111], v[242:243], off offset:2048
	global_load_dwordx4 v[112:115], v[242:243], off offset:2064
	v_lshl_add_u64 v[242:243], v[242:243], 0, s[62:63]
	s_waitcnt vmcnt(24)
	v_pk_fma_f32 v[16:17], v[210:211], v[126:127], v[16:17] op_sel_hi:[0,1,1]
	v_pk_fma_f32 v[14:15], v[210:211], v[128:129], v[14:15] op_sel_hi:[0,1,1]
	v_pk_fma_f32 v[12:13], v[210:211], v[130:131], v[12:13] op_sel_hi:[0,1,1]
	v_pk_fma_f32 v[10:11], v[210:211], v[132:133], v[10:11] op_sel_hi:[0,1,1]
	v_pk_fma_f32 v[16:17], v[212:213], v[134:135], v[16:17] op_sel_hi:[0,1,1]
	v_pk_fma_f32 v[14:15], v[212:213], v[136:137], v[14:15] op_sel_hi:[0,1,1]
	v_pk_fma_f32 v[12:13], v[212:213], v[138:139], v[12:13] op_sel_hi:[0,1,1]
	v_pk_fma_f32 v[10:11], v[212:213], v[140:141], v[10:11] op_sel_hi:[0,1,1]
	v_pk_fma_f32 v[16:17], v[214:215], v[142:143], v[16:17] op_sel_hi:[0,1,1]
	v_pk_fma_f32 v[14:15], v[214:215], v[144:145], v[14:15] op_sel_hi:[0,1,1]
	v_pk_fma_f32 v[12:13], v[214:215], v[146:147], v[12:13] op_sel_hi:[0,1,1]
	v_pk_fma_f32 v[10:11], v[214:215], v[148:149], v[10:11] op_sel_hi:[0,1,1]
	v_pk_fma_f32 v[16:17], v[216:217], v[150:151], v[16:17] op_sel_hi:[0,1,1]
	v_pk_fma_f32 v[14:15], v[216:217], v[152:153], v[14:15] op_sel_hi:[0,1,1]
	v_pk_fma_f32 v[12:13], v[216:217], v[154:155], v[12:13] op_sel_hi:[0,1,1]
	v_pk_fma_f32 v[10:11], v[216:217], v[156:157], v[10:11] op_sel_hi:[0,1,1]
	v_pk_fma_f32 v[16:17], v[218:219], v[158:159], v[16:17] op_sel_hi:[0,1,1]
	v_pk_fma_f32 v[14:15], v[218:219], v[160:161], v[14:15] op_sel_hi:[0,1,1]
	v_pk_fma_f32 v[12:13], v[218:219], v[162:163], v[12:13] op_sel_hi:[0,1,1]
	v_pk_fma_f32 v[10:11], v[218:219], v[164:165], v[10:11] op_sel_hi:[0,1,1]
	v_pk_fma_f32 v[16:17], v[220:221], v[166:167], v[16:17] op_sel_hi:[0,1,1]
	v_pk_fma_f32 v[14:15], v[220:221], v[168:169], v[14:15] op_sel_hi:[0,1,1]
	v_pk_fma_f32 v[12:13], v[220:221], v[170:171], v[12:13] op_sel_hi:[0,1,1]
	v_pk_fma_f32 v[10:11], v[220:221], v[172:173], v[10:11] op_sel_hi:[0,1,1]
	v_pk_fma_f32 v[16:17], v[222:223], v[174:175], v[16:17] op_sel_hi:[0,1,1]
	v_pk_fma_f32 v[14:15], v[222:223], v[176:177], v[14:15] op_sel_hi:[0,1,1]
	v_pk_fma_f32 v[12:13], v[222:223], v[178:179], v[12:13] op_sel_hi:[0,1,1]
	v_pk_fma_f32 v[10:11], v[222:223], v[180:181], v[10:11] op_sel_hi:[0,1,1]
	v_pk_fma_f32 v[16:17], v[224:225], v[182:183], v[16:17] op_sel_hi:[0,1,1]
	v_pk_fma_f32 v[14:15], v[224:225], v[184:185], v[14:15] op_sel_hi:[0,1,1]
	v_pk_fma_f32 v[12:13], v[224:225], v[186:187], v[12:13] op_sel_hi:[0,1,1]
	v_pk_fma_f32 v[10:11], v[224:225], v[188:189], v[10:11] op_sel_hi:[0,1,1]
	s_waitcnt vmcnt(0)
	v_pk_fma_f32 v[16:17], v[226:227], v[52:53], v[16:17] op_sel_hi:[0,1,1]
	v_pk_fma_f32 v[14:15], v[226:227], v[54:55], v[14:15] op_sel_hi:[0,1,1]
	v_pk_fma_f32 v[12:13], v[226:227], v[56:57], v[12:13] op_sel_hi:[0,1,1]
	v_pk_fma_f32 v[10:11], v[226:227], v[58:59], v[10:11] op_sel_hi:[0,1,1]
	v_pk_fma_f32 v[16:17], v[228:229], v[60:61], v[16:17] op_sel_hi:[0,1,1]
	v_pk_fma_f32 v[14:15], v[228:229], v[62:63], v[14:15] op_sel_hi:[0,1,1]
	v_pk_fma_f32 v[12:13], v[228:229], v[64:65], v[12:13] op_sel_hi:[0,1,1]
	v_pk_fma_f32 v[10:11], v[228:229], v[66:67], v[10:11] op_sel_hi:[0,1,1]
	v_pk_fma_f32 v[16:17], v[230:231], v[68:69], v[16:17] op_sel_hi:[0,1,1]
	v_pk_fma_f32 v[14:15], v[230:231], v[70:71], v[14:15] op_sel_hi:[0,1,1]
	v_pk_fma_f32 v[12:13], v[230:231], v[72:73], v[12:13] op_sel_hi:[0,1,1]
	v_pk_fma_f32 v[10:11], v[230:231], v[74:75], v[10:11] op_sel_hi:[0,1,1]
	v_pk_fma_f32 v[16:17], v[232:233], v[76:77], v[16:17] op_sel_hi:[0,1,1]
	v_pk_fma_f32 v[14:15], v[232:233], v[78:79], v[14:15] op_sel_hi:[0,1,1]
	v_pk_fma_f32 v[12:13], v[232:233], v[80:81], v[12:13] op_sel_hi:[0,1,1]
	v_pk_fma_f32 v[10:11], v[232:233], v[82:83], v[10:11] op_sel_hi:[0,1,1]
	v_pk_fma_f32 v[16:17], v[234:235], v[84:85], v[16:17] op_sel_hi:[0,1,1]
	v_pk_fma_f32 v[14:15], v[234:235], v[86:87], v[14:15] op_sel_hi:[0,1,1]
	v_pk_fma_f32 v[12:13], v[234:235], v[88:89], v[12:13] op_sel_hi:[0,1,1]
	v_pk_fma_f32 v[10:11], v[234:235], v[90:91], v[10:11] op_sel_hi:[0,1,1]
	v_pk_fma_f32 v[16:17], v[236:237], v[92:93], v[16:17] op_sel_hi:[0,1,1]
	v_pk_fma_f32 v[14:15], v[236:237], v[94:95], v[14:15] op_sel_hi:[0,1,1]
	v_pk_fma_f32 v[12:13], v[236:237], v[96:97], v[12:13] op_sel_hi:[0,1,1]
	v_pk_fma_f32 v[10:11], v[236:237], v[98:99], v[10:11] op_sel_hi:[0,1,1]
	v_pk_fma_f32 v[16:17], v[238:239], v[100:101], v[16:17] op_sel_hi:[0,1,1]
	v_pk_fma_f32 v[14:15], v[238:239], v[102:103], v[14:15] op_sel_hi:[0,1,1]
	v_pk_fma_f32 v[12:13], v[238:239], v[104:105], v[12:13] op_sel_hi:[0,1,1]
	v_pk_fma_f32 v[10:11], v[238:239], v[106:107], v[10:11] op_sel_hi:[0,1,1]
	v_pk_fma_f32 v[16:17], v[240:241], v[108:109], v[16:17] op_sel_hi:[0,1,1]
	v_pk_fma_f32 v[14:15], v[240:241], v[110:111], v[14:15] op_sel_hi:[0,1,1]
	v_pk_fma_f32 v[12:13], v[240:241], v[112:113], v[12:13] op_sel_hi:[0,1,1]
	v_pk_fma_f32 v[10:11], v[240:241], v[114:115], v[10:11] op_sel_hi:[0,1,1]
	s_and_saveexec_b64 s[12:13], vcc
	s_cbranch_execz .LBB0_49
	v_lshl_add_u64 v[18:19], v[6:7], 0, v[18:19]
	s_mov_b64 s[14:15], 0
	s_mov_b32 s62, 0x1000
	s_mov_b32 s63, 0
	s_mov_b32 s64, 0x10000
	s_mov_b32 s65, 0
	v_lshl_add_u64 v[242:243], v[4:5], 0, s[64:65]
	global_load_dword v210, v[18:19], off
	global_load_dword v212, v[18:19], off offset:256
	global_load_dword v214, v[18:19], off offset:512
	global_load_dword v216, v[18:19], off offset:768
	global_load_dword v218, v[18:19], off offset:1024
	global_load_dword v220, v[18:19], off offset:1280
	global_load_dword v222, v[18:19], off offset:1536
	global_load_dword v224, v[18:19], off offset:1792
	v_lshl_add_u64 v[18:19], v[18:19], 0, s[8:9]
	global_load_dwordx4 v[126:129], v[242:243], off
	global_load_dwordx4 v[130:133], v[242:243], off offset:16
	global_load_dwordx4 v[134:137], v[242:243], off offset:2048
	global_load_dwordx4 v[138:141], v[242:243], off offset:2064
	v_lshl_add_u64 v[242:243], v[242:243], 0, s[62:63]
	global_load_dwordx4 v[142:145], v[242:243], off
	global_load_dwordx4 v[146:149], v[242:243], off offset:16
	global_load_dwordx4 v[150:153], v[242:243], off offset:2048
	global_load_dwordx4 v[154:157], v[242:243], off offset:2064
	v_lshl_add_u64 v[242:243], v[242:243], 0, s[62:63]
	global_load_dwordx4 v[158:161], v[242:243], off
	global_load_dwordx4 v[162:165], v[242:243], off offset:16
	global_load_dwordx4 v[166:169], v[242:243], off offset:2048
	global_load_dwordx4 v[170:173], v[242:243], off offset:2064
	v_lshl_add_u64 v[242:243], v[242:243], 0, s[62:63]
	global_load_dwordx4 v[174:177], v[242:243], off
	global_load_dwordx4 v[178:181], v[242:243], off offset:16
	global_load_dwordx4 v[182:185], v[242:243], off offset:2048
	global_load_dwordx4 v[186:189], v[242:243], off offset:2064
	v_lshl_add_u64 v[242:243], v[242:243], 0, s[62:63]
	global_load_dword v226, v[18:19], off
	global_load_dword v228, v[18:19], off offset:256
	global_load_dword v230, v[18:19], off offset:512
	global_load_dword v232, v[18:19], off offset:768
	global_load_dword v234, v[18:19], off offset:1024
	global_load_dword v236, v[18:19], off offset:1280
	global_load_dword v238, v[18:19], off offset:1536
	global_load_dword v240, v[18:19], off offset:1792
	v_lshl_add_u64 v[18:19], v[18:19], 0, s[8:9]
	global_load_dwordx4 v[52:55], v[242:243], off
	global_load_dwordx4 v[56:59], v[242:243], off offset:16
	global_load_dwordx4 v[60:63], v[242:243], off offset:2048
	global_load_dwordx4 v[64:67], v[242:243], off offset:2064
	v_lshl_add_u64 v[242:243], v[242:243], 0, s[62:63]
	global_load_dwordx4 v[68:71], v[242:243], off
	global_load_dwordx4 v[72:75], v[242:243], off offset:16
	global_load_dwordx4 v[76:79], v[242:243], off offset:2048
	global_load_dwordx4 v[80:83], v[242:243], off offset:2064
	v_lshl_add_u64 v[242:243], v[242:243], 0, s[62:63]
	global_load_dwordx4 v[84:87], v[242:243], off
	global_load_dwordx4 v[88:91], v[242:243], off offset:16
	global_load_dwordx4 v[92:95], v[242:243], off offset:2048
	global_load_dwordx4 v[96:99], v[242:243], off offset:2064
	v_lshl_add_u64 v[242:243], v[242:243], 0, s[62:63]
	global_load_dwordx4 v[100:103], v[242:243], off
	global_load_dwordx4 v[104:107], v[242:243], off offset:16
	global_load_dwordx4 v[108:111], v[242:243], off offset:2048
	global_load_dwordx4 v[112:115], v[242:243], off offset:2064
	v_lshl_add_u64 v[242:243], v[242:243], 0, s[62:63]
	s_waitcnt vmcnt(24)
	v_pk_fma_f32 v[16:17], v[210:211], v[126:127], v[16:17] op_sel_hi:[0,1,1]
	v_pk_fma_f32 v[14:15], v[210:211], v[128:129], v[14:15] op_sel_hi:[0,1,1]
	v_pk_fma_f32 v[12:13], v[210:211], v[130:131], v[12:13] op_sel_hi:[0,1,1]
	v_pk_fma_f32 v[10:11], v[210:211], v[132:133], v[10:11] op_sel_hi:[0,1,1]
	v_pk_fma_f32 v[16:17], v[212:213], v[134:135], v[16:17] op_sel_hi:[0,1,1]
	v_pk_fma_f32 v[14:15], v[212:213], v[136:137], v[14:15] op_sel_hi:[0,1,1]
	v_pk_fma_f32 v[12:13], v[212:213], v[138:139], v[12:13] op_sel_hi:[0,1,1]
	v_pk_fma_f32 v[10:11], v[212:213], v[140:141], v[10:11] op_sel_hi:[0,1,1]
	v_pk_fma_f32 v[16:17], v[214:215], v[142:143], v[16:17] op_sel_hi:[0,1,1]
	v_pk_fma_f32 v[14:15], v[214:215], v[144:145], v[14:15] op_sel_hi:[0,1,1]
	v_pk_fma_f32 v[12:13], v[214:215], v[146:147], v[12:13] op_sel_hi:[0,1,1]
	v_pk_fma_f32 v[10:11], v[214:215], v[148:149], v[10:11] op_sel_hi:[0,1,1]
	v_pk_fma_f32 v[16:17], v[216:217], v[150:151], v[16:17] op_sel_hi:[0,1,1]
	v_pk_fma_f32 v[14:15], v[216:217], v[152:153], v[14:15] op_sel_hi:[0,1,1]
	v_pk_fma_f32 v[12:13], v[216:217], v[154:155], v[12:13] op_sel_hi:[0,1,1]
	v_pk_fma_f32 v[10:11], v[216:217], v[156:157], v[10:11] op_sel_hi:[0,1,1]
	v_pk_fma_f32 v[16:17], v[218:219], v[158:159], v[16:17] op_sel_hi:[0,1,1]
	v_pk_fma_f32 v[14:15], v[218:219], v[160:161], v[14:15] op_sel_hi:[0,1,1]
	v_pk_fma_f32 v[12:13], v[218:219], v[162:163], v[12:13] op_sel_hi:[0,1,1]
	v_pk_fma_f32 v[10:11], v[218:219], v[164:165], v[10:11] op_sel_hi:[0,1,1]
	v_pk_fma_f32 v[16:17], v[220:221], v[166:167], v[16:17] op_sel_hi:[0,1,1]
	v_pk_fma_f32 v[14:15], v[220:221], v[168:169], v[14:15] op_sel_hi:[0,1,1]
	v_pk_fma_f32 v[12:13], v[220:221], v[170:171], v[12:13] op_sel_hi:[0,1,1]
	v_pk_fma_f32 v[10:11], v[220:221], v[172:173], v[10:11] op_sel_hi:[0,1,1]
	v_pk_fma_f32 v[16:17], v[222:223], v[174:175], v[16:17] op_sel_hi:[0,1,1]
	v_pk_fma_f32 v[14:15], v[222:223], v[176:177], v[14:15] op_sel_hi:[0,1,1]
	v_pk_fma_f32 v[12:13], v[222:223], v[178:179], v[12:13] op_sel_hi:[0,1,1]
	v_pk_fma_f32 v[10:11], v[222:223], v[180:181], v[10:11] op_sel_hi:[0,1,1]
	v_pk_fma_f32 v[16:17], v[224:225], v[182:183], v[16:17] op_sel_hi:[0,1,1]
	v_pk_fma_f32 v[14:15], v[224:225], v[184:185], v[14:15] op_sel_hi:[0,1,1]
	v_pk_fma_f32 v[12:13], v[224:225], v[186:187], v[12:13] op_sel_hi:[0,1,1]
	v_pk_fma_f32 v[10:11], v[224:225], v[188:189], v[10:11] op_sel_hi:[0,1,1]
	global_load_dword v210, v[18:19], off
	global_load_dword v212, v[18:19], off offset:256
	global_load_dword v214, v[18:19], off offset:512
	global_load_dword v216, v[18:19], off offset:768
	global_load_dword v218, v[18:19], off offset:1024
	global_load_dword v220, v[18:19], off offset:1280
	global_load_dword v222, v[18:19], off offset:1536
	global_load_dword v224, v[18:19], off offset:1792
	v_lshl_add_u64 v[18:19], v[18:19], 0, s[8:9]
	global_load_dwordx4 v[126:129], v[242:243], off
	global_load_dwordx4 v[130:133], v[242:243], off offset:16
	global_load_dwordx4 v[134:137], v[242:243], off offset:2048
	global_load_dwordx4 v[138:141], v[242:243], off offset:2064
	v_lshl_add_u64 v[242:243], v[242:243], 0, s[62:63]
	global_load_dwordx4 v[142:145], v[242:243], off
	global_load_dwordx4 v[146:149], v[242:243], off offset:16
	global_load_dwordx4 v[150:153], v[242:243], off offset:2048
	global_load_dwordx4 v[154:157], v[242:243], off offset:2064
	v_lshl_add_u64 v[242:243], v[242:243], 0, s[62:63]
	global_load_dwordx4 v[158:161], v[242:243], off
	global_load_dwordx4 v[162:165], v[242:243], off offset:16
	global_load_dwordx4 v[166:169], v[242:243], off offset:2048
	global_load_dwordx4 v[170:173], v[242:243], off offset:2064
	v_lshl_add_u64 v[242:243], v[242:243], 0, s[62:63]
	global_load_dwordx4 v[174:177], v[242:243], off
	global_load_dwordx4 v[178:181], v[242:243], off offset:16
	global_load_dwordx4 v[182:185], v[242:243], off offset:2048
	global_load_dwordx4 v[186:189], v[242:243], off offset:2064
	v_lshl_add_u64 v[242:243], v[242:243], 0, s[62:63]
	s_waitcnt vmcnt(24)
	v_pk_fma_f32 v[16:17], v[226:227], v[52:53], v[16:17] op_sel_hi:[0,1,1]
	v_pk_fma_f32 v[14:15], v[226:227], v[54:55], v[14:15] op_sel_hi:[0,1,1]
	v_pk_fma_f32 v[12:13], v[226:227], v[56:57], v[12:13] op_sel_hi:[0,1,1]
	v_pk_fma_f32 v[10:11], v[226:227], v[58:59], v[10:11] op_sel_hi:[0,1,1]
	v_pk_fma_f32 v[16:17], v[228:229], v[60:61], v[16:17] op_sel_hi:[0,1,1]
	v_pk_fma_f32 v[14:15], v[228:229], v[62:63], v[14:15] op_sel_hi:[0,1,1]
	v_pk_fma_f32 v[12:13], v[228:229], v[64:65], v[12:13] op_sel_hi:[0,1,1]
	v_pk_fma_f32 v[10:11], v[228:229], v[66:67], v[10:11] op_sel_hi:[0,1,1]
	v_pk_fma_f32 v[16:17], v[230:231], v[68:69], v[16:17] op_sel_hi:[0,1,1]
	v_pk_fma_f32 v[14:15], v[230:231], v[70:71], v[14:15] op_sel_hi:[0,1,1]
	v_pk_fma_f32 v[12:13], v[230:231], v[72:73], v[12:13] op_sel_hi:[0,1,1]
	v_pk_fma_f32 v[10:11], v[230:231], v[74:75], v[10:11] op_sel_hi:[0,1,1]
	v_pk_fma_f32 v[16:17], v[232:233], v[76:77], v[16:17] op_sel_hi:[0,1,1]
	v_pk_fma_f32 v[14:15], v[232:233], v[78:79], v[14:15] op_sel_hi:[0,1,1]
	v_pk_fma_f32 v[12:13], v[232:233], v[80:81], v[12:13] op_sel_hi:[0,1,1]
	v_pk_fma_f32 v[10:11], v[232:233], v[82:83], v[10:11] op_sel_hi:[0,1,1]
	v_pk_fma_f32 v[16:17], v[234:235], v[84:85], v[16:17] op_sel_hi:[0,1,1]
	v_pk_fma_f32 v[14:15], v[234:235], v[86:87], v[14:15] op_sel_hi:[0,1,1]
	v_pk_fma_f32 v[12:13], v[234:235], v[88:89], v[12:13] op_sel_hi:[0,1,1]
	v_pk_fma_f32 v[10:11], v[234:235], v[90:91], v[10:11] op_sel_hi:[0,1,1]
	v_pk_fma_f32 v[16:17], v[236:237], v[92:93], v[16:17] op_sel_hi:[0,1,1]
	v_pk_fma_f32 v[14:15], v[236:237], v[94:95], v[14:15] op_sel_hi:[0,1,1]
	v_pk_fma_f32 v[12:13], v[236:237], v[96:97], v[12:13] op_sel_hi:[0,1,1]
	v_pk_fma_f32 v[10:11], v[236:237], v[98:99], v[10:11] op_sel_hi:[0,1,1]
	v_pk_fma_f32 v[16:17], v[238:239], v[100:101], v[16:17] op_sel_hi:[0,1,1]
	v_pk_fma_f32 v[14:15], v[238:239], v[102:103], v[14:15] op_sel_hi:[0,1,1]
	v_pk_fma_f32 v[12:13], v[238:239], v[104:105], v[12:13] op_sel_hi:[0,1,1]
	v_pk_fma_f32 v[10:11], v[238:239], v[106:107], v[10:11] op_sel_hi:[0,1,1]
	v_pk_fma_f32 v[16:17], v[240:241], v[108:109], v[16:17] op_sel_hi:[0,1,1]
	v_pk_fma_f32 v[14:15], v[240:241], v[110:111], v[14:15] op_sel_hi:[0,1,1]
	v_pk_fma_f32 v[12:13], v[240:241], v[112:113], v[12:13] op_sel_hi:[0,1,1]
	v_pk_fma_f32 v[10:11], v[240:241], v[114:115], v[10:11] op_sel_hi:[0,1,1]
	global_load_dword v226, v[18:19], off
	global_load_dword v228, v[18:19], off offset:256
	global_load_dword v230, v[18:19], off offset:512
	global_load_dword v232, v[18:19], off offset:768
	global_load_dword v234, v[18:19], off offset:1024
	global_load_dword v236, v[18:19], off offset:1280
	global_load_dword v238, v[18:19], off offset:1536
	global_load_dword v240, v[18:19], off offset:1792
	v_lshl_add_u64 v[18:19], v[18:19], 0, s[8:9]
	global_load_dwordx4 v[52:55], v[242:243], off
	global_load_dwordx4 v[56:59], v[242:243], off offset:16
	global_load_dwordx4 v[60:63], v[242:243], off offset:2048
	global_load_dwordx4 v[64:67], v[242:243], off offset:2064
	v_lshl_add_u64 v[242:243], v[242:243], 0, s[62:63]
	global_load_dwordx4 v[68:71], v[242:243], off
	global_load_dwordx4 v[72:75], v[242:243], off offset:16
	global_load_dwordx4 v[76:79], v[242:243], off offset:2048
	global_load_dwordx4 v[80:83], v[242:243], off offset:2064
	v_lshl_add_u64 v[242:243], v[242:243], 0, s[62:63]
	global_load_dwordx4 v[84:87], v[242:243], off
	global_load_dwordx4 v[88:91], v[242:243], off offset:16
	global_load_dwordx4 v[92:95], v[242:243], off offset:2048
	global_load_dwordx4 v[96:99], v[242:243], off offset:2064
	v_lshl_add_u64 v[242:243], v[242:243], 0, s[62:63]
	global_load_dwordx4 v[100:103], v[242:243], off
	global_load_dwordx4 v[104:107], v[242:243], off offset:16
	global_load_dwordx4 v[108:111], v[242:243], off offset:2048
	global_load_dwordx4 v[112:115], v[242:243], off offset:2064
	v_lshl_add_u64 v[242:243], v[242:243], 0, s[62:63]
	s_waitcnt vmcnt(24)
	v_pk_fma_f32 v[16:17], v[210:211], v[126:127], v[16:17] op_sel_hi:[0,1,1]
	v_pk_fma_f32 v[14:15], v[210:211], v[128:129], v[14:15] op_sel_hi:[0,1,1]
	v_pk_fma_f32 v[12:13], v[210:211], v[130:131], v[12:13] op_sel_hi:[0,1,1]
	v_pk_fma_f32 v[10:11], v[210:211], v[132:133], v[10:11] op_sel_hi:[0,1,1]
	v_pk_fma_f32 v[16:17], v[212:213], v[134:135], v[16:17] op_sel_hi:[0,1,1]
	v_pk_fma_f32 v[14:15], v[212:213], v[136:137], v[14:15] op_sel_hi:[0,1,1]
	v_pk_fma_f32 v[12:13], v[212:213], v[138:139], v[12:13] op_sel_hi:[0,1,1]
	v_pk_fma_f32 v[10:11], v[212:213], v[140:141], v[10:11] op_sel_hi:[0,1,1]
	v_pk_fma_f32 v[16:17], v[214:215], v[142:143], v[16:17] op_sel_hi:[0,1,1]
	v_pk_fma_f32 v[14:15], v[214:215], v[144:145], v[14:15] op_sel_hi:[0,1,1]
	v_pk_fma_f32 v[12:13], v[214:215], v[146:147], v[12:13] op_sel_hi:[0,1,1]
	v_pk_fma_f32 v[10:11], v[214:215], v[148:149], v[10:11] op_sel_hi:[0,1,1]
	v_pk_fma_f32 v[16:17], v[216:217], v[150:151], v[16:17] op_sel_hi:[0,1,1]
	v_pk_fma_f32 v[14:15], v[216:217], v[152:153], v[14:15] op_sel_hi:[0,1,1]
	v_pk_fma_f32 v[12:13], v[216:217], v[154:155], v[12:13] op_sel_hi:[0,1,1]
	v_pk_fma_f32 v[10:11], v[216:217], v[156:157], v[10:11] op_sel_hi:[0,1,1]
	v_pk_fma_f32 v[16:17], v[218:219], v[158:159], v[16:17] op_sel_hi:[0,1,1]
	v_pk_fma_f32 v[14:15], v[218:219], v[160:161], v[14:15] op_sel_hi:[0,1,1]
	v_pk_fma_f32 v[12:13], v[218:219], v[162:163], v[12:13] op_sel_hi:[0,1,1]
	v_pk_fma_f32 v[10:11], v[218:219], v[164:165], v[10:11] op_sel_hi:[0,1,1]
	v_pk_fma_f32 v[16:17], v[220:221], v[166:167], v[16:17] op_sel_hi:[0,1,1]
	v_pk_fma_f32 v[14:15], v[220:221], v[168:169], v[14:15] op_sel_hi:[0,1,1]
	v_pk_fma_f32 v[12:13], v[220:221], v[170:171], v[12:13] op_sel_hi:[0,1,1]
	v_pk_fma_f32 v[10:11], v[220:221], v[172:173], v[10:11] op_sel_hi:[0,1,1]
	v_pk_fma_f32 v[16:17], v[222:223], v[174:175], v[16:17] op_sel_hi:[0,1,1]
	v_pk_fma_f32 v[14:15], v[222:223], v[176:177], v[14:15] op_sel_hi:[0,1,1]
	v_pk_fma_f32 v[12:13], v[222:223], v[178:179], v[12:13] op_sel_hi:[0,1,1]
	v_pk_fma_f32 v[10:11], v[222:223], v[180:181], v[10:11] op_sel_hi:[0,1,1]
	v_pk_fma_f32 v[16:17], v[224:225], v[182:183], v[16:17] op_sel_hi:[0,1,1]
	v_pk_fma_f32 v[14:15], v[224:225], v[184:185], v[14:15] op_sel_hi:[0,1,1]
	v_pk_fma_f32 v[12:13], v[224:225], v[186:187], v[12:13] op_sel_hi:[0,1,1]
	v_pk_fma_f32 v[10:11], v[224:225], v[188:189], v[10:11] op_sel_hi:[0,1,1]
	s_waitcnt vmcnt(0)
	v_pk_fma_f32 v[16:17], v[226:227], v[52:53], v[16:17] op_sel_hi:[0,1,1]
	v_pk_fma_f32 v[14:15], v[226:227], v[54:55], v[14:15] op_sel_hi:[0,1,1]
	v_pk_fma_f32 v[12:13], v[226:227], v[56:57], v[12:13] op_sel_hi:[0,1,1]
	v_pk_fma_f32 v[10:11], v[226:227], v[58:59], v[10:11] op_sel_hi:[0,1,1]
	v_pk_fma_f32 v[16:17], v[228:229], v[60:61], v[16:17] op_sel_hi:[0,1,1]
	v_pk_fma_f32 v[14:15], v[228:229], v[62:63], v[14:15] op_sel_hi:[0,1,1]
	v_pk_fma_f32 v[12:13], v[228:229], v[64:65], v[12:13] op_sel_hi:[0,1,1]
	v_pk_fma_f32 v[10:11], v[228:229], v[66:67], v[10:11] op_sel_hi:[0,1,1]
	v_pk_fma_f32 v[16:17], v[230:231], v[68:69], v[16:17] op_sel_hi:[0,1,1]
	v_pk_fma_f32 v[14:15], v[230:231], v[70:71], v[14:15] op_sel_hi:[0,1,1]
	v_pk_fma_f32 v[12:13], v[230:231], v[72:73], v[12:13] op_sel_hi:[0,1,1]
	v_pk_fma_f32 v[10:11], v[230:231], v[74:75], v[10:11] op_sel_hi:[0,1,1]
	v_pk_fma_f32 v[16:17], v[232:233], v[76:77], v[16:17] op_sel_hi:[0,1,1]
	v_pk_fma_f32 v[14:15], v[232:233], v[78:79], v[14:15] op_sel_hi:[0,1,1]
	v_pk_fma_f32 v[12:13], v[232:233], v[80:81], v[12:13] op_sel_hi:[0,1,1]
	v_pk_fma_f32 v[10:11], v[232:233], v[82:83], v[10:11] op_sel_hi:[0,1,1]
	v_pk_fma_f32 v[16:17], v[234:235], v[84:85], v[16:17] op_sel_hi:[0,1,1]
	v_pk_fma_f32 v[14:15], v[234:235], v[86:87], v[14:15] op_sel_hi:[0,1,1]
	v_pk_fma_f32 v[12:13], v[234:235], v[88:89], v[12:13] op_sel_hi:[0,1,1]
	v_pk_fma_f32 v[10:11], v[234:235], v[90:91], v[10:11] op_sel_hi:[0,1,1]
	v_pk_fma_f32 v[16:17], v[236:237], v[92:93], v[16:17] op_sel_hi:[0,1,1]
	v_pk_fma_f32 v[14:15], v[236:237], v[94:95], v[14:15] op_sel_hi:[0,1,1]
	v_pk_fma_f32 v[12:13], v[236:237], v[96:97], v[12:13] op_sel_hi:[0,1,1]
	v_pk_fma_f32 v[10:11], v[236:237], v[98:99], v[10:11] op_sel_hi:[0,1,1]
	v_pk_fma_f32 v[16:17], v[238:239], v[100:101], v[16:17] op_sel_hi:[0,1,1]
	v_pk_fma_f32 v[14:15], v[238:239], v[102:103], v[14:15] op_sel_hi:[0,1,1]
	v_pk_fma_f32 v[12:13], v[238:239], v[104:105], v[12:13] op_sel_hi:[0,1,1]
	v_pk_fma_f32 v[10:11], v[238:239], v[106:107], v[10:11] op_sel_hi:[0,1,1]
	v_pk_fma_f32 v[16:17], v[240:241], v[108:109], v[16:17] op_sel_hi:[0,1,1]
	v_pk_fma_f32 v[14:15], v[240:241], v[110:111], v[14:15] op_sel_hi:[0,1,1]
	v_pk_fma_f32 v[12:13], v[240:241], v[112:113], v[12:13] op_sel_hi:[0,1,1]
	v_pk_fma_f32 v[10:11], v[240:241], v[114:115], v[10:11] op_sel_hi:[0,1,1]
